# v16 + differential-attention unit epilogue: the 16 sub-LN gain loads hoisted ahead of the stores, counted vmcnt(15) instead of 16 serialized store-drain + load round trips
# baseline (speedup 1.0000x reference)
; __device__ __forceinline__ void diff_unit(int b, int hd, int qb, const bf16_t* Q, const bf16_t* K, const bf16_t* VT, bf16_t* O, const float* biasd, float lam, const float* subg, ALAS unsigned char* lds) {
;     ...
;     if (map == 1) {
; #pragma unroll
;         for (int d = 0; d < 4; ++d)
; #pragma unroll
;             for (int r = 0; r < 16; ++r) X[((w4 * 4 + d) * 16 + r) * 64 + lane] = o[d][r] * inv;
;     }
;     __syncthreads();
;     if (map == 0) {
;         float sq = 0.f;
; #pragma unroll
;         for (int d = 0; d < 4; ++d)
; #pragma unroll
;             for (int r = 0; r < 16; ++r) { const float a = o[d][r] * inv - lam * X[((w4 * 4 + d) * 16 + r) * 64 + lane]; o[d][r] = a; sq += a * a; }
;         sq += __shfl_xor(sq, 32);
;         const float rn = __builtin_amdgcn_rsqf(sq * (1.0f / 128.0f) + SUBLN_EPS) * 0.8f;
;         bf16_t* op = O + (tok0 + qpos) * 1024 + hd * 128 + 4 * hi;
; #pragma unroll
;         for (int d = 0; d < 4; ++d)
; #pragma unroll
;             for (int a4 = 0; a4 < 4; ++a4) { const int c0 = d * 32 + 8 * a4; const pg8::f32x4 g4 = *(const pg8::f32x4*)(subg + c0 + 4 * hi); u32x2 w;
.LBB0_514:
	s_cmpk_gt_u32 s7, 0xff
	s_waitcnt lgkmcnt(0)
	s_barrier
	s_cbranch_scc1 .LBB0_494
	s_lshl_b32 s4, s7, 8
	v_lshl_add_u32 v68, v64, 2, 0
	s_and_b32 s7, s4, 0xc000
	v_add_u32_e32 v69, s7, v68
	ds_read2st64_b32 v[108:109], v69 offset1:1
	ds_read2st64_b32 v[106:107], v69 offset0:2 offset1:3
	s_waitcnt vmcnt(2)
	ds_read2st64_b32 v[122:123], v69 offset0:4 offset1:5
	ds_read2st64_b32 v[114:115], v69 offset0:6 offset1:7
	s_waitcnt vmcnt(0)
	ds_read2st64_b32 v[124:125], v69 offset0:8 offset1:9
	ds_read2st64_b32 v[156:157], v69 offset0:10 offset1:11
	ds_read2st64_b32 v[138:139], v69 offset0:12 offset1:13
	ds_read2st64_b32 v[142:143], v69 offset0:14 offset1:15
	ds_read2st64_b32 v[126:127], v69 offset0:16 offset1:17
	ds_read2st64_b32 v[140:141], v69 offset0:18 offset1:19
	ds_read2st64_b32 v[118:119], v69 offset0:20 offset1:21
	ds_read2st64_b32 v[136:137], v69 offset0:22 offset1:23
	ds_read2st64_b32 v[110:111], v69 offset0:24 offset1:25
	ds_read2st64_b32 v[120:121], v69 offset0:26 offset1:27
	ds_read2st64_b32 v[100:101], v69 offset0:28 offset1:29
	ds_read2st64_b32 v[112:113], v69 offset0:30 offset1:31
	ds_read2st64_b32 v[96:97], v69 offset0:32 offset1:33
	ds_read2st64_b32 v[104:105], v69 offset0:34 offset1:35
	ds_read2st64_b32 v[92:93], v69 offset0:36 offset1:37
	ds_read2st64_b32 v[98:99], v69 offset0:38 offset1:39
	ds_read2st64_b32 v[88:89], v69 offset0:40 offset1:41
	ds_read2st64_b32 v[94:95], v69 offset0:42 offset1:43
	ds_read2st64_b32 v[86:87], v69 offset0:44 offset1:45
	ds_read2st64_b32 v[90:91], v69 offset0:46 offset1:47
	ds_read2st64_b32 v[82:83], v69 offset0:48 offset1:49
	ds_read2st64_b32 v[84:85], v69 offset0:50 offset1:51
	ds_read2st64_b32 v[76:77], v69 offset0:52 offset1:53
	ds_read2st64_b32 v[80:81], v69 offset0:54 offset1:55
	ds_read2st64_b32 v[74:75], v69 offset0:56 offset1:57
	ds_read2st64_b32 v[64:65], v69 offset0:58 offset1:59
	s_waitcnt lgkmcnt(14)
	v_pk_mul_f32 v[106:107], v[128:129], v[106:107]
	s_or_b32 s4, s4, 0x3f00
	v_pk_fma_f32 v[106:107], v[50:51], v[70:71], v[106:107] op_sel_hi:[1,0,1] neg_lo:[0,0,1] neg_hi:[0,0,1]
	v_pk_mul_f32 v[50:51], v[128:129], v[108:109]
	s_waitcnt lgkmcnt(0)
	v_pk_mul_f32 v[64:65], v[128:129], v[64:65]
	v_pk_fma_f32 v[116:117], v[48:49], v[70:71], v[50:51] op_sel_hi:[1,0,1] neg_lo:[0,0,1] neg_hi:[0,0,1]
	v_pk_mul_f32 v[48:49], v[128:129], v[114:115]
	v_pk_fma_f32 v[64:65], v[10:11], v[70:71], v[64:65] op_sel_hi:[1,0,1] neg_lo:[0,0,1] neg_hi:[0,0,1]
	v_pk_fma_f32 v[114:115], v[54:55], v[70:71], v[48:49] op_sel_hi:[1,0,1] neg_lo:[0,0,1] neg_hi:[0,0,1]
	v_pk_mul_f32 v[48:49], v[128:129], v[122:123]
	ds_read2st64_b32 v[10:11], v69 offset0:60 offset1:61
	v_pk_fma_f32 v[122:123], v[52:53], v[70:71], v[48:49] op_sel_hi:[1,0,1] neg_lo:[0,0,1] neg_hi:[0,0,1]
	v_pk_mul_f32 v[48:49], v[128:129], v[156:157]
	v_mov_b32_e32 v135, v145
	v_pk_fma_f32 v[108:109], v[58:59], v[70:71], v[48:49] op_sel_hi:[1,0,1] neg_lo:[0,0,1] neg_hi:[0,0,1]
	v_pk_mul_f32 v[48:49], v[128:129], v[124:125]
	s_waitcnt lgkmcnt(0)
	v_pk_mul_f32 v[10:11], v[128:129], v[10:11]
	v_pk_fma_f32 v[124:125], v[56:57], v[70:71], v[48:49] op_sel_hi:[1,0,1] neg_lo:[0,0,1] neg_hi:[0,0,1]
	v_pk_mul_f32 v[48:49], v[128:129], v[142:143]
	v_pk_fma_f32 v[66:67], v[12:13], v[70:71], v[10:11] op_sel_hi:[1,0,1] neg_lo:[0,0,1] neg_hi:[0,0,1]
	v_pk_fma_f32 v[56:57], v[62:63], v[70:71], v[48:49] op_sel_hi:[1,0,1] neg_lo:[0,0,1] neg_hi:[0,0,1]
	v_pk_mul_f32 v[48:49], v[128:129], v[138:139]
	v_add_u32_e32 v11, s4, v68
	v_pk_fma_f32 v[60:61], v[60:61], v[70:71], v[48:49] op_sel_hi:[1,0,1] neg_lo:[0,0,1] neg_hi:[0,0,1]
	v_pk_mul_f32 v[48:49], v[128:129], v[140:141]
	ds_read_b32 v10, v69 offset:15872
	ds_read_b32 v11, v11
	v_pk_fma_f32 v[52:53], v[34:35], v[70:71], v[48:49] op_sel_hi:[1,0,1] neg_lo:[0,0,1] neg_hi:[0,0,1]
	v_pk_mul_f32 v[34:35], v[128:129], v[126:127]
	s_lshl_b32 s4, s6, 1
	v_pk_fma_f32 v[58:59], v[32:33], v[70:71], v[34:35] op_sel_hi:[1,0,1] neg_lo:[0,0,1] neg_hi:[0,0,1]
	v_pk_mul_f32 v[32:33], v[128:129], v[136:137]
	s_waitcnt lgkmcnt(0)
	v_pk_mul_f32 v[10:11], v[128:129], v[10:11]
	v_pk_fma_f32 v[48:49], v[38:39], v[70:71], v[32:33] op_sel_hi:[1,0,1] neg_lo:[0,0,1] neg_hi:[0,0,1]
	v_pk_mul_f32 v[32:33], v[128:129], v[118:119]
	v_pk_fma_f32 v[68:69], v[14:15], v[70:71], v[10:11] op_sel_hi:[1,0,1] neg_lo:[0,0,1] neg_hi:[0,0,1]
	v_pk_fma_f32 v[54:55], v[36:37], v[70:71], v[32:33] op_sel_hi:[1,0,1] neg_lo:[0,0,1] neg_hi:[0,0,1]
	v_pk_mul_f32 v[32:33], v[128:129], v[120:121]
	v_lshl_add_u64 v[10:11], v[132:133], 1, s[92:93]
	v_pk_fma_f32 v[42:43], v[42:43], v[70:71], v[32:33] op_sel_hi:[1,0,1] neg_lo:[0,0,1] neg_hi:[0,0,1]
	v_pk_mul_f32 v[32:33], v[128:129], v[110:111]
	v_lshl_add_u64 v[10:11], v[10:11], 0, s[4:5]
	v_pk_fma_f32 v[50:51], v[40:41], v[70:71], v[32:33] op_sel_hi:[1,0,1] neg_lo:[0,0,1] neg_hi:[0,0,1]
	v_pk_mul_f32 v[32:33], v[128:129], v[112:113]
	v_lshl_add_u64 v[14:15], v[10:11], 0, v[134:135]
	v_pk_fma_f32 v[38:39], v[46:47], v[70:71], v[32:33] op_sel_hi:[1,0,1] neg_lo:[0,0,1] neg_hi:[0,0,1]
	v_pk_mul_f32 v[32:33], v[128:129], v[100:101]
	global_load_dwordx4 v[10:13], v130, s[76:77]
	global_load_dwordx4 v[172:175], v130, s[76:77] offset:32
	global_load_dwordx4 v[176:179], v130, s[76:77] offset:64
	global_load_dwordx4 v[180:183], v130, s[76:77] offset:96
	global_load_dwordx4 v[184:187], v130, s[76:77] offset:128
	global_load_dwordx4 v[188:191], v130, s[76:77] offset:160
	global_load_dwordx4 v[192:195], v130, s[76:77] offset:192
	global_load_dwordx4 v[196:199], v130, s[76:77] offset:224
	global_load_dwordx4 v[216:219], v130, s[76:77] offset:256
	global_load_dwordx4 v[220:223], v130, s[76:77] offset:288
; __device__ __forceinline__ void diff_unit(int b, int hd, int qb, const bf16_t* Q, const bf16_t* K, const bf16_t* VT, bf16_t* O, const float* biasd, float lam, const float* subg, ALAS unsigned char* lds) {
;     ...
;             for (int r = 0; r < 16; ++r) { const float a = o[d][r] * inv - lam * X[((w4 * 4 + d) * 16 + r) * 64 + lane]; o[d][r] = a; sq += a * a; }
;         sq += __shfl_xor(sq, 32);
;         const float rn = __builtin_amdgcn_rsqf(sq * (1.0f / 128.0f) + SUBLN_EPS) * 0.8f;
;         bf16_t* op = O + (tok0 + qpos) * 1024 + hd * 128 + 4 * hi;
; #pragma unroll
;         for (int d = 0; d < 4; ++d)
; #pragma unroll
;             for (int a4 = 0; a4 < 4; ++a4) { const int c0 = d * 32 + 8 * a4; const pg8::f32x4 g4 = *(const pg8::f32x4*)(subg + c0 + 4 * hi); u32x2 w;
	global_load_dwordx4 v[224:227], v130, s[76:77] offset:320
	global_load_dwordx4 v[228:231], v130, s[76:77] offset:352
	global_load_dwordx4 v[232:235], v130, s[76:77] offset:384
	global_load_dwordx4 v[236:239], v130, s[76:77] offset:416
	global_load_dwordx4 v[240:243], v130, s[76:77] offset:448
	global_load_dwordx4 v[244:247], v130, s[76:77] offset:480
	v_pk_fma_f32 v[44:45], v[44:45], v[70:71], v[32:33] op_sel_hi:[1,0,1] neg_lo:[0,0,1] neg_hi:[0,0,1]
	v_pk_mul_f32 v[32:33], v[128:129], v[104:105]
	v_pk_mul_f32 v[134:135], v[116:117], v[116:117]
	v_pk_fma_f32 v[34:35], v[18:19], v[70:71], v[32:33] op_sel_hi:[1,0,1] neg_lo:[0,0,1] neg_hi:[0,0,1]
	v_pk_mul_f32 v[18:19], v[128:129], v[96:97]
	v_pk_mul_f32 v[132:133], v[106:107], v[106:107]
	v_pk_fma_f32 v[40:41], v[16:17], v[70:71], v[18:19] op_sel_hi:[1,0,1] neg_lo:[0,0,1] neg_hi:[0,0,1]
	v_pk_mul_f32 v[16:17], v[128:129], v[98:99]
	v_pk_mul_f32 v[160:161], v[122:123], v[122:123]
	v_pk_fma_f32 v[32:33], v[22:23], v[70:71], v[16:17] op_sel_hi:[1,0,1] neg_lo:[0,0,1] neg_hi:[0,0,1]
	v_pk_mul_f32 v[16:17], v[128:129], v[92:93]
	v_pk_mul_f32 v[158:159], v[114:115], v[114:115]
	v_pk_fma_f32 v[36:37], v[20:21], v[70:71], v[16:17] op_sel_hi:[1,0,1] neg_lo:[0,0,1] neg_hi:[0,0,1]
	v_pk_mul_f32 v[16:17], v[128:129], v[94:95]
	v_pk_mul_f32 v[162:163], v[124:125], v[124:125]
	v_pk_fma_f32 v[22:23], v[26:27], v[70:71], v[16:17] op_sel_hi:[1,0,1] neg_lo:[0,0,1] neg_hi:[0,0,1]
	v_pk_mul_f32 v[16:17], v[128:129], v[88:89]
	v_pk_mul_f32 v[156:157], v[108:109], v[108:109]
	v_pk_fma_f32 v[26:27], v[24:25], v[70:71], v[16:17] op_sel_hi:[1,0,1] neg_lo:[0,0,1] neg_hi:[0,0,1]
	v_pk_mul_f32 v[16:17], v[128:129], v[90:91]
	v_pk_mul_f32 v[138:139], v[60:61], v[60:61]
	v_pk_fma_f32 v[18:19], v[30:31], v[70:71], v[16:17] op_sel_hi:[1,0,1] neg_lo:[0,0,1] neg_hi:[0,0,1]
	v_pk_mul_f32 v[16:17], v[128:129], v[86:87]
	v_pk_mul_f32 v[62:63], v[56:57], v[56:57]
	v_pk_fma_f32 v[24:25], v[28:29], v[70:71], v[16:17] op_sel_hi:[1,0,1] neg_lo:[0,0,1] neg_hi:[0,0,1]
	v_pk_mul_f32 v[16:17], v[128:129], v[84:85]
	v_pk_mul_f32 v[126:127], v[58:59], v[58:59]
	v_pk_fma_f32 v[16:17], v[2:3], v[70:71], v[16:17] op_sel_hi:[1,0,1] neg_lo:[0,0,1] neg_hi:[0,0,1]
	v_pk_mul_f32 v[2:3], v[128:129], v[82:83]
	v_pk_mul_f32 v[140:141], v[52:53], v[52:53]
	v_pk_fma_f32 v[20:21], v[0:1], v[70:71], v[2:3] op_sel_hi:[1,0,1] neg_lo:[0,0,1] neg_hi:[0,0,1]
	v_pk_mul_f32 v[0:1], v[128:129], v[80:81]
	v_pk_mul_f32 v[118:119], v[54:55], v[54:55]
	v_pk_fma_f32 v[2:3], v[6:7], v[70:71], v[0:1] op_sel_hi:[1,0,1] neg_lo:[0,0,1] neg_hi:[0,0,1]
	v_pk_mul_f32 v[0:1], v[128:129], v[76:77]
	v_pk_mul_f32 v[136:137], v[48:49], v[48:49]
	v_pk_fma_f32 v[4:5], v[4:5], v[70:71], v[0:1] op_sel_hi:[1,0,1] neg_lo:[0,0,1] neg_hi:[0,0,1]
	v_pk_mul_f32 v[0:1], v[128:129], v[74:75]
	v_pk_mul_f32 v[110:111], v[50:51], v[50:51]
	v_pk_fma_f32 v[0:1], v[8:9], v[70:71], v[0:1] op_sel_hi:[1,0,1] neg_lo:[0,0,1] neg_hi:[0,0,1]
	v_add_f32_e32 v70, v134, v135
	v_add_f32_e32 v70, v70, v132
	v_add_f32_e32 v70, v70, v133
	v_add_f32_e32 v70, v70, v160
	v_add_f32_e32 v70, v70, v161
	v_add_f32_e32 v70, v70, v158
	v_add_f32_e32 v70, v70, v159
	v_add_f32_e32 v70, v70, v162
	v_add_f32_e32 v70, v70, v163
	v_add_f32_e32 v70, v70, v156
	v_add_f32_e32 v70, v70, v157
	v_add_f32_e32 v70, v70, v138
	v_add_f32_e32 v70, v70, v139
	v_add_f32_e32 v62, v70, v62
	v_add_f32_e32 v62, v62, v63
	v_add_f32_e32 v62, v62, v126
	v_add_f32_e32 v62, v62, v127
	v_add_f32_e32 v62, v62, v140
	v_add_f32_e32 v62, v62, v141
	v_add_f32_e32 v62, v62, v118
	v_add_f32_e32 v62, v62, v119
	v_add_f32_e32 v62, v62, v136
	v_add_f32_e32 v62, v62, v137
	v_add_f32_e32 v62, v62, v110
	v_pk_mul_f32 v[120:121], v[42:43], v[42:43]
	v_add_f32_e32 v62, v62, v111
	v_add_f32_e32 v62, v62, v120
	v_pk_mul_f32 v[100:101], v[44:45], v[44:45]
	v_add_f32_e32 v62, v62, v121
	v_add_f32_e32 v62, v62, v100
	v_pk_mul_f32 v[46:47], v[38:39], v[38:39]
	v_add_f32_e32 v62, v62, v101
	v_add_f32_e32 v46, v62, v46
	v_pk_mul_f32 v[96:97], v[40:41], v[40:41]
	v_add_f32_e32 v46, v46, v47
	v_add_f32_e32 v46, v46, v96
	v_pk_mul_f32 v[104:105], v[34:35], v[34:35]
	v_add_f32_e32 v46, v46, v97
	v_add_f32_e32 v46, v46, v104
	v_pk_mul_f32 v[92:93], v[36:37], v[36:37]
	v_add_f32_e32 v46, v46, v105
	v_add_f32_e32 v46, v46, v92
	v_pk_mul_f32 v[98:99], v[32:33], v[32:33]
	v_add_f32_e32 v46, v46, v93
	v_add_f32_e32 v46, v46, v98
	v_pk_mul_f32 v[88:89], v[26:27], v[26:27]
	v_add_f32_e32 v46, v46, v99
	v_add_f32_e32 v46, v46, v88
	v_pk_mul_f32 v[94:95], v[22:23], v[22:23]
	v_add_f32_e32 v46, v46, v89
	v_add_f32_e32 v46, v46, v94
	v_pk_mul_f32 v[28:29], v[24:25], v[24:25]
	v_add_f32_e32 v46, v46, v95
	v_add_f32_e32 v28, v46, v28
	v_pk_mul_f32 v[30:31], v[18:19], v[18:19]
	v_add_f32_e32 v28, v28, v29
	v_add_f32_e32 v28, v28, v30
	v_pk_mul_f32 v[82:83], v[20:21], v[20:21]
	v_add_f32_e32 v28, v28, v31
	v_add_f32_e32 v28, v28, v82
	v_pk_mul_f32 v[84:85], v[16:17], v[16:17]
	v_add_f32_e32 v28, v28, v83
	v_add_f32_e32 v28, v28, v84
	v_pk_mul_f32 v[76:77], v[4:5], v[4:5]
	v_add_f32_e32 v28, v28, v85
	v_add_f32_e32 v28, v28, v76
	v_pk_mul_f32 v[6:7], v[2:3], v[2:3]
	v_add_f32_e32 v28, v28, v77
	v_add_f32_e32 v6, v28, v6
	v_pk_mul_f32 v[8:9], v[0:1], v[0:1]
	v_add_f32_e32 v6, v6, v7
	v_add_f32_e32 v6, v6, v8
	v_pk_mul_f32 v[72:73], v[64:65], v[64:65]
	v_add_f32_e32 v6, v6, v9
	v_add_f32_e32 v6, v6, v72
	v_pk_mul_f32 v[78:79], v[66:67], v[66:67]
	v_add_f32_e32 v6, v6, v73
	v_add_f32_e32 v6, v6, v78
	v_pk_mul_f32 v[102:103], v[68:69], v[68:69]
	v_add_f32_e32 v6, v6, v79
	v_add_f32_e32 v6, v6, v102
	v_add_f32_e32 v6, v6, v103
	ds_bpermute_b32 v7, v170, v6
	s_waitcnt lgkmcnt(0)
; __device__ __forceinline__ unsigned cvtpk(float lo, float hi) { return pg8::cvt_pk_bf16(lo, hi); }
; __device__ __forceinline__ void diff_unit(int b, int hd, int qb, const bf16_t* Q, const bf16_t* K, const bf16_t* VT, bf16_t* O, const float* biasd, float lam, const float* subg, ALAS unsigned char* lds) {
;     ...
;         sq += __shfl_xor(sq, 32);
;         const float rn = __builtin_amdgcn_rsqf(sq * (1.0f / 128.0f) + SUBLN_EPS) * 0.8f;
;         bf16_t* op = O + (tok0 + qpos) * 1024 + hd * 128 + 4 * hi;
; #pragma unroll
;         for (int d = 0; d < 4; ++d)
; #pragma unroll
;             for (int a4 = 0; a4 < 4; ++a4) { const int c0 = d * 32 + 8 * a4; const pg8::f32x4 g4 = *(const pg8::f32x4*)(subg + c0 + 4 * hi); u32x2 w;
;                 w.x = cvtpk(o[d][4 * a4 + 0] * rn * g4[0], o[d][4 * a4 + 1] * rn * g4[1]); w.y = cvtpk(o[d][4 * a4 + 2] * rn * g4[2], o[d][4 * a4 + 3] * rn * g4[3]);
;                 *(u32x2*)(op + c0) = w; }
	v_add_f32_e32 v6, v6, v7
	v_mov_b32_e32 v7, 0x3727c5ac
	v_fmamk_f32 v6, v6, 0x3c000000, v7
	v_rsq_f32_e32 v6, v6
	s_nop 0
	v_mul_f32_e32 v6, 0x3f4ccccd, v6
	v_pk_mul_f32 v[8:9], v[116:117], v[6:7] op_sel_hi:[1,0]
	v_pk_mul_f32 v[4:5], v[4:5], v[6:7] op_sel_hi:[1,0]
	s_waitcnt vmcnt(15)
	v_pk_mul_f32 v[8:9], v[10:11], v[8:9]
	v_pk_mul_f32 v[10:11], v[106:107], v[6:7] op_sel_hi:[1,0]
	v_cvt_pk_bf16_f32 v8, v8, v9
	v_pk_mul_f32 v[10:11], v[12:13], v[10:11]
	v_pk_mul_f32 v[12:13], v[122:123], v[6:7] op_sel_hi:[1,0]
	v_cvt_pk_bf16_f32 v9, v10, v11
	global_store_dwordx2 v[14:15], v[8:9], off
	v_pk_mul_f32 v[2:3], v[2:3], v[6:7] op_sel_hi:[1,0]
	v_pk_mul_f32 v[0:1], v[0:1], v[6:7] op_sel_hi:[1,0]
	s_waitcnt vmcnt(15)
	v_pk_mul_f32 v[8:9], v[172:173], v[12:13]
	v_pk_mul_f32 v[12:13], v[114:115], v[6:7] op_sel_hi:[1,0]
	v_cvt_pk_bf16_f32 v8, v8, v9
	v_pk_mul_f32 v[10:11], v[174:175], v[12:13]
	v_pk_mul_f32 v[12:13], v[124:125], v[6:7] op_sel_hi:[1,0]
	v_cvt_pk_bf16_f32 v9, v10, v11
	global_store_dwordx2 v[14:15], v[8:9], off offset:16
	s_waitcnt vmcnt(15)
	v_pk_mul_f32 v[8:9], v[176:177], v[12:13]
	v_pk_mul_f32 v[12:13], v[108:109], v[6:7] op_sel_hi:[1,0]
	v_cvt_pk_bf16_f32 v8, v8, v9
	v_pk_mul_f32 v[10:11], v[178:179], v[12:13]
	v_pk_mul_f32 v[12:13], v[60:61], v[6:7] op_sel_hi:[1,0]
	v_cvt_pk_bf16_f32 v9, v10, v11
	global_store_dwordx2 v[14:15], v[8:9], off offset:32
	s_waitcnt vmcnt(15)
	v_pk_mul_f32 v[8:9], v[180:181], v[12:13]
	v_pk_mul_f32 v[12:13], v[56:57], v[6:7] op_sel_hi:[1,0]
	v_cvt_pk_bf16_f32 v8, v8, v9
	v_pk_mul_f32 v[10:11], v[182:183], v[12:13]
	v_pk_mul_f32 v[12:13], v[58:59], v[6:7] op_sel_hi:[1,0]
	v_cvt_pk_bf16_f32 v9, v10, v11
	global_store_dwordx2 v[14:15], v[8:9], off offset:48
	s_waitcnt vmcnt(15)
	v_pk_mul_f32 v[8:9], v[184:185], v[12:13]
	v_pk_mul_f32 v[12:13], v[52:53], v[6:7] op_sel_hi:[1,0]
	v_cvt_pk_bf16_f32 v8, v8, v9
	v_pk_mul_f32 v[10:11], v[186:187], v[12:13]
	v_pk_mul_f32 v[12:13], v[54:55], v[6:7] op_sel_hi:[1,0]
	v_cvt_pk_bf16_f32 v9, v10, v11
	global_store_dwordx2 v[14:15], v[8:9], off offset:64
	s_waitcnt vmcnt(15)
	v_pk_mul_f32 v[8:9], v[12:13], v[188:189]
	v_pk_mul_f32 v[12:13], v[48:49], v[6:7] op_sel_hi:[1,0]
	v_cvt_pk_bf16_f32 v8, v8, v9
	v_pk_mul_f32 v[10:11], v[12:13], v[190:191]
	v_pk_mul_f32 v[12:13], v[50:51], v[6:7] op_sel_hi:[1,0]
	v_cvt_pk_bf16_f32 v9, v10, v11
	global_store_dwordx2 v[14:15], v[8:9], off offset:80
	s_waitcnt vmcnt(15)
	v_pk_mul_f32 v[8:9], v[12:13], v[192:193]
	v_pk_mul_f32 v[12:13], v[42:43], v[6:7] op_sel_hi:[1,0]
	v_cvt_pk_bf16_f32 v8, v8, v9
	v_pk_mul_f32 v[10:11], v[12:13], v[194:195]
	v_pk_mul_f32 v[12:13], v[44:45], v[6:7] op_sel_hi:[1,0]
	v_cvt_pk_bf16_f32 v9, v10, v11
	global_store_dwordx2 v[14:15], v[8:9], off offset:96
	s_waitcnt vmcnt(15)
	v_pk_mul_f32 v[8:9], v[12:13], v[196:197]
	v_pk_mul_f32 v[12:13], v[38:39], v[6:7] op_sel_hi:[1,0]
	v_cvt_pk_bf16_f32 v8, v8, v9
	v_pk_mul_f32 v[10:11], v[12:13], v[198:199]
	v_pk_mul_f32 v[12:13], v[40:41], v[6:7] op_sel_hi:[1,0]
	v_cvt_pk_bf16_f32 v9, v10, v11
	global_store_dwordx2 v[14:15], v[8:9], off offset:112
	s_waitcnt vmcnt(15)
	v_pk_mul_f32 v[8:9], v[12:13], v[216:217]
	v_pk_mul_f32 v[12:13], v[34:35], v[6:7] op_sel_hi:[1,0]
	v_cvt_pk_bf16_f32 v8, v8, v9
	v_pk_mul_f32 v[10:11], v[12:13], v[218:219]
	v_pk_mul_f32 v[12:13], v[36:37], v[6:7] op_sel_hi:[1,0]
	v_cvt_pk_bf16_f32 v9, v10, v11
	global_store_dwordx2 v[14:15], v[8:9], off offset:128
	s_waitcnt vmcnt(15)
	v_pk_mul_f32 v[8:9], v[12:13], v[220:221]
	v_pk_mul_f32 v[12:13], v[32:33], v[6:7] op_sel_hi:[1,0]
	v_cvt_pk_bf16_f32 v8, v8, v9
	v_pk_mul_f32 v[10:11], v[12:13], v[222:223]
	v_pk_mul_f32 v[12:13], v[26:27], v[6:7] op_sel_hi:[1,0]
	v_cvt_pk_bf16_f32 v9, v10, v11
	global_store_dwordx2 v[14:15], v[8:9], off offset:144
	s_waitcnt vmcnt(15)
	v_pk_mul_f32 v[8:9], v[12:13], v[224:225]
	v_pk_mul_f32 v[12:13], v[22:23], v[6:7] op_sel_hi:[1,0]
	v_cvt_pk_bf16_f32 v8, v8, v9
	v_pk_mul_f32 v[10:11], v[12:13], v[226:227]
	v_pk_mul_f32 v[12:13], v[24:25], v[6:7] op_sel_hi:[1,0]
	v_cvt_pk_bf16_f32 v9, v10, v11
	global_store_dwordx2 v[14:15], v[8:9], off offset:160
	s_waitcnt vmcnt(15)
	v_pk_mul_f32 v[8:9], v[12:13], v[228:229]
	v_pk_mul_f32 v[12:13], v[18:19], v[6:7] op_sel_hi:[1,0]
	v_cvt_pk_bf16_f32 v8, v8, v9
	v_pk_mul_f32 v[10:11], v[12:13], v[230:231]
	v_pk_mul_f32 v[12:13], v[20:21], v[6:7] op_sel_hi:[1,0]
	v_cvt_pk_bf16_f32 v9, v10, v11
	global_store_dwordx2 v[14:15], v[8:9], off offset:176
	s_waitcnt vmcnt(15)
	v_pk_mul_f32 v[8:9], v[12:13], v[232:233]
	v_pk_mul_f32 v[12:13], v[16:17], v[6:7] op_sel_hi:[1,0]
	v_cvt_pk_bf16_f32 v8, v8, v9
	v_pk_mul_f32 v[10:11], v[12:13], v[234:235]
	s_nop 0
	v_cvt_pk_bf16_f32 v9, v10, v11
	global_store_dwordx2 v[14:15], v[8:9], off offset:192
	s_waitcnt vmcnt(15)
	v_pk_mul_f32 v[4:5], v[4:5], v[236:237]
	v_pk_mul_f32 v[2:3], v[2:3], v[238:239]
	v_cvt_pk_bf16_f32 v4, v4, v5
	v_cvt_pk_bf16_f32 v5, v2, v3
	global_store_dwordx2 v[14:15], v[4:5], off offset:208
	s_waitcnt vmcnt(15)
	v_pk_mul_f32 v[0:1], v[0:1], v[240:241]
	v_pk_mul_f32 v[2:3], v[64:65], v[6:7] op_sel_hi:[1,0]
	v_cvt_pk_bf16_f32 v0, v0, v1
	v_pk_mul_f32 v[2:3], v[2:3], v[242:243]
	v_pk_mul_f32 v[4:5], v[66:67], v[6:7] op_sel_hi:[1,0]
	v_cvt_pk_bf16_f32 v1, v2, v3
	global_store_dwordx2 v[14:15], v[0:1], off offset:224
	s_waitcnt vmcnt(15)
	v_pk_mul_f32 v[0:1], v[4:5], v[244:245]
	v_pk_mul_f32 v[4:5], v[68:69], v[6:7] op_sel_hi:[1,0]
	v_cvt_pk_bf16_f32 v0, v0, v1
	v_pk_mul_f32 v[2:3], v[4:5], v[246:247]
	s_nop 0
	v_cvt_pk_bf16_f32 v1, v2, v3
	global_store_dwordx2 v[14:15], v[0:1], off offset:240
	s_branch .LBB0_494
